# v56 + phase 4b pass 2 rewritten: all 8 rows per thread requested up front (post_g loaded once), same per-row arithmetic
# speedup vs baseline: 1.0107x; 1.0022x over previous
.LBB0_606:
	s_or_b64 exec, exec, s[6:7]
	s_barrier
	s_barrier
	ds_write2_b32 v219, v108, v124 offset1:16
	v_add_u32_e32 v108, 0x400, v219
	ds_write2_b32 v108, v109, v125 offset0:4 offset1:20
	v_add_u32_e32 v109, 0x800, v219
	ds_write2_b32 v109, v110, v126 offset0:8 offset1:24
	v_add_u32_e32 v110, 0xc00, v219
	ds_write2_b32 v110, v111, v127 offset0:12 offset1:28
	v_add_u32_e32 v111, 0x4000, v219
	ds_write2_b32 v111, v80, v88 offset0:64 offset1:80
	v_add_u32_e32 v80, 0x4400, v219
	ds_write2_b32 v80, v81, v89 offset0:68 offset1:84
	v_add_u32_e32 v81, 0x4800, v219
	ds_write2_b32 v81, v82, v90 offset0:72 offset1:88
	v_add_u32_e32 v82, 0x4c00, v219
	ds_write2_b32 v82, v83, v91 offset0:76 offset1:92
	v_add_u32_e32 v83, 0x8000, v219
	ds_write2_b32 v83, v72, v76 offset0:128 offset1:144
	v_add_u32_e32 v72, 0x8400, v219
	ds_write2_b32 v72, v73, v77 offset0:132 offset1:148
	v_add_u32_e32 v73, 0x8800, v219
	ds_write2_b32 v73, v74, v78 offset0:136 offset1:152
	v_add_u32_e32 v74, 0x8c00, v219
	ds_write2_b32 v74, v75, v79 offset0:140 offset1:156
	v_add_u32_e32 v75, 0xc000, v219
	ds_write2_b32 v75, v64, v68 offset0:192 offset1:208
	v_add_u32_e32 v64, 0xc400, v219
	ds_write2_b32 v64, v65, v69 offset0:196 offset1:212
	v_add_u32_e32 v65, 0xc800, v219
	ds_write2_b32 v65, v66, v70 offset0:200 offset1:216
	v_add_u32_e32 v66, 0xcc00, v219
	ds_write2_b32 v66, v67, v71 offset0:204 offset1:220
	ds_write2_b32 v219, v96, v116 offset0:128 offset1:144
	ds_write2_b32 v108, v97, v117 offset0:132 offset1:148
	ds_write2_b32 v109, v98, v118 offset0:136 offset1:152
	ds_write2_b32 v110, v99, v119 offset0:140 offset1:156
	ds_write2_b32 v111, v100, v120 offset0:192 offset1:208
	ds_write2_b32 v80, v101, v121 offset0:196 offset1:212
	ds_write2_b32 v81, v102, v122 offset0:200 offset1:216
	ds_write2_b32 v82, v103, v123 offset0:204 offset1:220
	ds_write2_b32 v72, v92, v112 offset1:16
	ds_write2_b32 v73, v93, v113 offset0:4 offset1:20
	ds_write2_b32 v74, v94, v114 offset0:8 offset1:24
	v_add_u32_e32 v67, 0x9000, v219
	ds_write2_b32 v67, v95, v115 offset0:12 offset1:28
	ds_write2_b32 v64, v84, v104 offset0:64 offset1:80
	ds_write2_b32 v65, v85, v105 offset0:68 offset1:84
	ds_write2_b32 v66, v86, v106 offset0:72 offset1:88
	v_add_u32_e32 v64, 0xd000, v219
	v_ashrrev_i32_e32 v129, 6, v140
	ds_write2_b32 v64, v87, v107 offset0:76 offset1:92
	s_waitcnt lgkmcnt(0)
	s_barrier
	s_load_dwordx4 s[8:11], s[0:1], 0x80
	s_load_dwordx2 s[6:7], s[0:1], 0x0
	v_lshlrev_b32_e32 v132, 7, v129
	v_lshlrev_b32_e32 v131, 3, v131
	v_and_b32_e32 v129, 0x80, v132
	v_and_b32_e32 v131, 0x78, v131
	v_or3_b32 v129, v129, s62, v131
	v_lshlrev_b32_e32 v68, 2, v129
	v_mov_b32_e32 v69, 0
	s_waitcnt lgkmcnt(0)
	v_lshl_add_u64 v[64:65], s[8:9], 0, v[68:69]
	v_lshl_add_u64 v[66:67], s[6:7], 0, v[68:69]
	v_lshl_add_u64 v[68:69], s[10:11], 0, v[68:69]
	s_mov_b32 s6, 0
	v_mov_b32_e32 v70, 0x358637bd
	s_mov_b32 s7, 0x800000
	global_load_dwordx4 v[72:75], v[64:65], off
	global_load_dwordx4 v[76:79], v[64:65], off offset:16
	v_add_u32_e32 v94, 0, v130
	v_ashrrev_i32_e32 v95, 31, v94
	v_lshl_add_u64 v[92:93], v[94:95], 2, s[2:3]
	v_lshlrev_b64 v[94:95], 12, v[94:95]
	global_load_dword v204, v[92:93], off sc1
	v_lshl_add_u64 v[94:95], v[66:67], 0, v[94:95]
	global_load_dwordx4 v[140:143], v[94:95], off
	global_load_dwordx4 v[144:147], v[94:95], off offset:16
	v_add_u32_e32 v94, 4, v130
	v_ashrrev_i32_e32 v95, 31, v94
	v_lshl_add_u64 v[92:93], v[94:95], 2, s[2:3]
	v_lshlrev_b64 v[94:95], 12, v[94:95]
	global_load_dword v205, v[92:93], off sc1
	v_lshl_add_u64 v[94:95], v[66:67], 0, v[94:95]
	global_load_dwordx4 v[148:151], v[94:95], off
	global_load_dwordx4 v[152:155], v[94:95], off offset:16
	v_add_u32_e32 v94, 8, v130
	v_ashrrev_i32_e32 v95, 31, v94
	v_lshl_add_u64 v[92:93], v[94:95], 2, s[2:3]
	v_lshlrev_b64 v[94:95], 12, v[94:95]
	global_load_dword v206, v[92:93], off sc1
	v_lshl_add_u64 v[94:95], v[66:67], 0, v[94:95]
	global_load_dwordx4 v[156:159], v[94:95], off
	global_load_dwordx4 v[160:163], v[94:95], off offset:16
	v_add_u32_e32 v94, 12, v130
	v_ashrrev_i32_e32 v95, 31, v94
	v_lshl_add_u64 v[92:93], v[94:95], 2, s[2:3]
	v_lshlrev_b64 v[94:95], 12, v[94:95]
	global_load_dword v207, v[92:93], off sc1
	v_lshl_add_u64 v[94:95], v[66:67], 0, v[94:95]
	global_load_dwordx4 v[164:167], v[94:95], off
	global_load_dwordx4 v[168:171], v[94:95], off offset:16
	v_add_u32_e32 v94, 16, v130
	v_ashrrev_i32_e32 v95, 31, v94
	v_lshl_add_u64 v[92:93], v[94:95], 2, s[2:3]
	v_lshlrev_b64 v[94:95], 12, v[94:95]
	global_load_dword v208, v[92:93], off sc1
	v_lshl_add_u64 v[94:95], v[66:67], 0, v[94:95]
	global_load_dwordx4 v[172:175], v[94:95], off
	global_load_dwordx4 v[176:179], v[94:95], off offset:16
	v_add_u32_e32 v94, 20, v130
	v_ashrrev_i32_e32 v95, 31, v94
	v_lshl_add_u64 v[92:93], v[94:95], 2, s[2:3]
	v_lshlrev_b64 v[94:95], 12, v[94:95]
	global_load_dword v209, v[92:93], off sc1
	v_lshl_add_u64 v[94:95], v[66:67], 0, v[94:95]
	global_load_dwordx4 v[180:183], v[94:95], off
	global_load_dwordx4 v[184:187], v[94:95], off offset:16
	v_add_u32_e32 v94, 24, v130
	v_ashrrev_i32_e32 v95, 31, v94
	v_lshl_add_u64 v[92:93], v[94:95], 2, s[2:3]
	v_lshlrev_b64 v[94:95], 12, v[94:95]
	global_load_dword v210, v[92:93], off sc1
	v_lshl_add_u64 v[94:95], v[66:67], 0, v[94:95]
	global_load_dwordx4 v[188:191], v[94:95], off
	global_load_dwordx4 v[192:195], v[94:95], off offset:16
	v_add_u32_e32 v94, 28, v130
	v_ashrrev_i32_e32 v95, 31, v94
	v_lshl_add_u64 v[92:93], v[94:95], 2, s[2:3]
	v_lshlrev_b64 v[94:95], 12, v[94:95]
	global_load_dword v211, v[92:93], off sc1
	v_lshl_add_u64 v[94:95], v[66:67], 0, v[94:95]
	global_load_dwordx4 v[196:199], v[94:95], off
	global_load_dwordx4 v[200:203], v[94:95], off offset:16
	ds_read_b128 v[80:83], v136 offset:0
	ds_read_b128 v[84:87], v136 offset:16
	v_add_u32_e32 v90, 0, v130
	v_ashrrev_i32_e32 v91, 31, v90
	v_lshlrev_b64 v[90:91], 12, v[90:91]
	v_lshl_add_u64 v[90:91], v[68:69], 0, v[90:91]
	s_waitcnt vmcnt(21)
	v_fmamk_f32 v88, v204, 0x3a800000, v70
	v_mul_f32_e32 v89, 0x4b800000, v88
	v_cmp_gt_f32_e32 vcc, s7, v88
	s_nop 1
	v_cndmask_b32_e32 v88, v88, v89, vcc
	v_rsq_f32_e32 v88, v88
	s_nop 0
	v_mul_f32_e32 v89, 0x45800000, v88
	v_cndmask_b32_e32 v88, v88, v89, vcc
	s_waitcnt lgkmcnt(0)
	v_pk_mul_f32 v[80:81], v[80:81], v[88:89] op_sel_hi:[1,0]
	v_pk_mul_f32 v[82:83], v[82:83], v[88:89] op_sel_hi:[1,0]
	v_pk_mul_f32 v[84:85], v[84:85], v[88:89] op_sel_hi:[1,0]
	v_pk_mul_f32 v[86:87], v[86:87], v[88:89] op_sel_hi:[1,0]
	v_pk_fma_f32 v[80:81], v[72:73], v[80:81], v[140:141]
	v_pk_fma_f32 v[82:83], v[74:75], v[82:83], v[142:143]
	v_pk_fma_f32 v[84:85], v[76:77], v[84:85], v[144:145]
	v_pk_fma_f32 v[86:87], v[78:79], v[86:87], v[146:147]
	global_store_dwordx4 v[90:91], v[80:83], off
	global_store_dwordx4 v[90:91], v[84:87], off offset:16
	ds_read_b128 v[96:99], v136 offset:4160
	ds_read_b128 v[100:103], v136 offset:4176
	v_add_u32_e32 v106, 4, v130
	v_ashrrev_i32_e32 v107, 31, v106
	v_lshlrev_b64 v[106:107], 12, v[106:107]
	v_lshl_add_u64 v[106:107], v[68:69], 0, v[106:107]
	s_waitcnt vmcnt(20)
	v_fmamk_f32 v104, v205, 0x3a800000, v70
	v_mul_f32_e32 v105, 0x4b800000, v104
	v_cmp_gt_f32_e32 vcc, s7, v104
	s_nop 1
	v_cndmask_b32_e32 v104, v104, v105, vcc
	v_rsq_f32_e32 v104, v104
	s_nop 0
	v_mul_f32_e32 v105, 0x45800000, v104
	v_cndmask_b32_e32 v104, v104, v105, vcc
	s_waitcnt lgkmcnt(0)
	v_pk_mul_f32 v[96:97], v[96:97], v[104:105] op_sel_hi:[1,0]
	v_pk_mul_f32 v[98:99], v[98:99], v[104:105] op_sel_hi:[1,0]
	v_pk_mul_f32 v[100:101], v[100:101], v[104:105] op_sel_hi:[1,0]
	v_pk_mul_f32 v[102:103], v[102:103], v[104:105] op_sel_hi:[1,0]
	v_pk_fma_f32 v[96:97], v[72:73], v[96:97], v[148:149]
	v_pk_fma_f32 v[98:99], v[74:75], v[98:99], v[150:151]
	v_pk_fma_f32 v[100:101], v[76:77], v[100:101], v[152:153]
	v_pk_fma_f32 v[102:103], v[78:79], v[102:103], v[154:155]
	global_store_dwordx4 v[106:107], v[96:99], off
	global_store_dwordx4 v[106:107], v[100:103], off offset:16
	ds_read_b128 v[80:83], v136 offset:8320
	ds_read_b128 v[84:87], v136 offset:8336
	v_add_u32_e32 v90, 8, v130
	v_ashrrev_i32_e32 v91, 31, v90
	v_lshlrev_b64 v[90:91], 12, v[90:91]
	v_lshl_add_u64 v[90:91], v[68:69], 0, v[90:91]
	s_waitcnt vmcnt(19)
	v_fmamk_f32 v88, v206, 0x3a800000, v70
	v_mul_f32_e32 v89, 0x4b800000, v88
	v_cmp_gt_f32_e32 vcc, s7, v88
	s_nop 1
	v_cndmask_b32_e32 v88, v88, v89, vcc
	v_rsq_f32_e32 v88, v88
	s_nop 0
	v_mul_f32_e32 v89, 0x45800000, v88
	v_cndmask_b32_e32 v88, v88, v89, vcc
	s_waitcnt lgkmcnt(0)
	v_pk_mul_f32 v[80:81], v[80:81], v[88:89] op_sel_hi:[1,0]
	v_pk_mul_f32 v[82:83], v[82:83], v[88:89] op_sel_hi:[1,0]
	v_pk_mul_f32 v[84:85], v[84:85], v[88:89] op_sel_hi:[1,0]
	v_pk_mul_f32 v[86:87], v[86:87], v[88:89] op_sel_hi:[1,0]
	v_pk_fma_f32 v[80:81], v[72:73], v[80:81], v[156:157]
	v_pk_fma_f32 v[82:83], v[74:75], v[82:83], v[158:159]
	v_pk_fma_f32 v[84:85], v[76:77], v[84:85], v[160:161]
	v_pk_fma_f32 v[86:87], v[78:79], v[86:87], v[162:163]
	global_store_dwordx4 v[90:91], v[80:83], off
	global_store_dwordx4 v[90:91], v[84:87], off offset:16
	ds_read_b128 v[96:99], v136 offset:12480
	ds_read_b128 v[100:103], v136 offset:12496
	v_add_u32_e32 v106, 12, v130
	v_ashrrev_i32_e32 v107, 31, v106
	v_lshlrev_b64 v[106:107], 12, v[106:107]
	v_lshl_add_u64 v[106:107], v[68:69], 0, v[106:107]
	s_waitcnt vmcnt(18)
	v_fmamk_f32 v104, v207, 0x3a800000, v70
	v_mul_f32_e32 v105, 0x4b800000, v104
	v_cmp_gt_f32_e32 vcc, s7, v104
	s_nop 1
	v_cndmask_b32_e32 v104, v104, v105, vcc
	v_rsq_f32_e32 v104, v104
	s_nop 0
	v_mul_f32_e32 v105, 0x45800000, v104
	v_cndmask_b32_e32 v104, v104, v105, vcc
	s_waitcnt lgkmcnt(0)
	v_pk_mul_f32 v[96:97], v[96:97], v[104:105] op_sel_hi:[1,0]
	v_pk_mul_f32 v[98:99], v[98:99], v[104:105] op_sel_hi:[1,0]
	v_pk_mul_f32 v[100:101], v[100:101], v[104:105] op_sel_hi:[1,0]
	v_pk_mul_f32 v[102:103], v[102:103], v[104:105] op_sel_hi:[1,0]
	v_pk_fma_f32 v[96:97], v[72:73], v[96:97], v[164:165]
	v_pk_fma_f32 v[98:99], v[74:75], v[98:99], v[166:167]
	v_pk_fma_f32 v[100:101], v[76:77], v[100:101], v[168:169]
	v_pk_fma_f32 v[102:103], v[78:79], v[102:103], v[170:171]
	global_store_dwordx4 v[106:107], v[96:99], off
	global_store_dwordx4 v[106:107], v[100:103], off offset:16
	ds_read_b128 v[80:83], v136 offset:16640
	ds_read_b128 v[84:87], v136 offset:16656
	v_add_u32_e32 v90, 16, v130
	v_ashrrev_i32_e32 v91, 31, v90
	v_lshlrev_b64 v[90:91], 12, v[90:91]
	v_lshl_add_u64 v[90:91], v[68:69], 0, v[90:91]
	s_waitcnt vmcnt(17)
	v_fmamk_f32 v88, v208, 0x3a800000, v70
	v_mul_f32_e32 v89, 0x4b800000, v88
	v_cmp_gt_f32_e32 vcc, s7, v88
	s_nop 1
	v_cndmask_b32_e32 v88, v88, v89, vcc
	v_rsq_f32_e32 v88, v88
	s_nop 0
	v_mul_f32_e32 v89, 0x45800000, v88
	v_cndmask_b32_e32 v88, v88, v89, vcc
	s_waitcnt lgkmcnt(0)
	v_pk_mul_f32 v[80:81], v[80:81], v[88:89] op_sel_hi:[1,0]
	v_pk_mul_f32 v[82:83], v[82:83], v[88:89] op_sel_hi:[1,0]
	v_pk_mul_f32 v[84:85], v[84:85], v[88:89] op_sel_hi:[1,0]
	v_pk_mul_f32 v[86:87], v[86:87], v[88:89] op_sel_hi:[1,0]
	v_pk_fma_f32 v[80:81], v[72:73], v[80:81], v[172:173]
	v_pk_fma_f32 v[82:83], v[74:75], v[82:83], v[174:175]
	v_pk_fma_f32 v[84:85], v[76:77], v[84:85], v[176:177]
	v_pk_fma_f32 v[86:87], v[78:79], v[86:87], v[178:179]
	global_store_dwordx4 v[90:91], v[80:83], off
	global_store_dwordx4 v[90:91], v[84:87], off offset:16
	ds_read_b128 v[96:99], v136 offset:20800
	ds_read_b128 v[100:103], v136 offset:20816
	v_add_u32_e32 v106, 20, v130
	v_ashrrev_i32_e32 v107, 31, v106
	v_lshlrev_b64 v[106:107], 12, v[106:107]
	v_lshl_add_u64 v[106:107], v[68:69], 0, v[106:107]
	s_waitcnt vmcnt(16)
	v_fmamk_f32 v104, v209, 0x3a800000, v70
	v_mul_f32_e32 v105, 0x4b800000, v104
	v_cmp_gt_f32_e32 vcc, s7, v104
	s_nop 1
	v_cndmask_b32_e32 v104, v104, v105, vcc
	v_rsq_f32_e32 v104, v104
	s_nop 0
	v_mul_f32_e32 v105, 0x45800000, v104
	v_cndmask_b32_e32 v104, v104, v105, vcc
	s_waitcnt lgkmcnt(0)
	v_pk_mul_f32 v[96:97], v[96:97], v[104:105] op_sel_hi:[1,0]
	v_pk_mul_f32 v[98:99], v[98:99], v[104:105] op_sel_hi:[1,0]
	v_pk_mul_f32 v[100:101], v[100:101], v[104:105] op_sel_hi:[1,0]
	v_pk_mul_f32 v[102:103], v[102:103], v[104:105] op_sel_hi:[1,0]
	v_pk_fma_f32 v[96:97], v[72:73], v[96:97], v[180:181]
	v_pk_fma_f32 v[98:99], v[74:75], v[98:99], v[182:183]
	v_pk_fma_f32 v[100:101], v[76:77], v[100:101], v[184:185]
	v_pk_fma_f32 v[102:103], v[78:79], v[102:103], v[186:187]
	global_store_dwordx4 v[106:107], v[96:99], off
	global_store_dwordx4 v[106:107], v[100:103], off offset:16
	ds_read_b128 v[80:83], v136 offset:24960
	ds_read_b128 v[84:87], v136 offset:24976
	v_add_u32_e32 v90, 24, v130
	v_ashrrev_i32_e32 v91, 31, v90
	v_lshlrev_b64 v[90:91], 12, v[90:91]
	v_lshl_add_u64 v[90:91], v[68:69], 0, v[90:91]
	s_waitcnt vmcnt(15)
	v_fmamk_f32 v88, v210, 0x3a800000, v70
	v_mul_f32_e32 v89, 0x4b800000, v88
	v_cmp_gt_f32_e32 vcc, s7, v88
	s_nop 1
	v_cndmask_b32_e32 v88, v88, v89, vcc
	v_rsq_f32_e32 v88, v88
	s_nop 0
	v_mul_f32_e32 v89, 0x45800000, v88
	v_cndmask_b32_e32 v88, v88, v89, vcc
	s_waitcnt lgkmcnt(0)
	v_pk_mul_f32 v[80:81], v[80:81], v[88:89] op_sel_hi:[1,0]
	v_pk_mul_f32 v[82:83], v[82:83], v[88:89] op_sel_hi:[1,0]
	v_pk_mul_f32 v[84:85], v[84:85], v[88:89] op_sel_hi:[1,0]
	v_pk_mul_f32 v[86:87], v[86:87], v[88:89] op_sel_hi:[1,0]
	v_pk_fma_f32 v[80:81], v[72:73], v[80:81], v[188:189]
	v_pk_fma_f32 v[82:83], v[74:75], v[82:83], v[190:191]
	v_pk_fma_f32 v[84:85], v[76:77], v[84:85], v[192:193]
	v_pk_fma_f32 v[86:87], v[78:79], v[86:87], v[194:195]
	global_store_dwordx4 v[90:91], v[80:83], off
	global_store_dwordx4 v[90:91], v[84:87], off offset:16
	ds_read_b128 v[96:99], v136 offset:29120
	ds_read_b128 v[100:103], v136 offset:29136
	v_add_u32_e32 v106, 28, v130
	v_ashrrev_i32_e32 v107, 31, v106
	v_lshlrev_b64 v[106:107], 12, v[106:107]
	v_lshl_add_u64 v[106:107], v[68:69], 0, v[106:107]
	s_waitcnt vmcnt(14)
	v_fmamk_f32 v104, v211, 0x3a800000, v70
	v_mul_f32_e32 v105, 0x4b800000, v104
	v_cmp_gt_f32_e32 vcc, s7, v104
	s_nop 1
	v_cndmask_b32_e32 v104, v104, v105, vcc
	v_rsq_f32_e32 v104, v104
	s_nop 0
	v_mul_f32_e32 v105, 0x45800000, v104
	v_cndmask_b32_e32 v104, v104, v105, vcc
	s_waitcnt lgkmcnt(0)
	v_pk_mul_f32 v[96:97], v[96:97], v[104:105] op_sel_hi:[1,0]
	v_pk_mul_f32 v[98:99], v[98:99], v[104:105] op_sel_hi:[1,0]
	v_pk_mul_f32 v[100:101], v[100:101], v[104:105] op_sel_hi:[1,0]
	v_pk_mul_f32 v[102:103], v[102:103], v[104:105] op_sel_hi:[1,0]
	v_pk_fma_f32 v[96:97], v[72:73], v[96:97], v[196:197]
	v_pk_fma_f32 v[98:99], v[74:75], v[98:99], v[198:199]
	v_pk_fma_f32 v[100:101], v[76:77], v[100:101], v[200:201]
	v_pk_fma_f32 v[102:103], v[78:79], v[102:103], v[202:203]
	global_store_dwordx4 v[106:107], v[96:99], off
	global_store_dwordx4 v[106:107], v[100:103], off offset:16
	s_waitcnt lgkmcnt(0)
	s_barrier
	ds_write2_b32 v219, v56, v60 offset1:16
	v_add_u32_e32 v56, 0x400, v219
	ds_write2_b32 v56, v57, v61 offset0:4 offset1:20
	v_add_u32_e32 v57, 0x800, v219
	ds_write2_b32 v57, v58, v62 offset0:8 offset1:24
	v_add_u32_e32 v58, 0xc00, v219
	ds_write2_b32 v58, v59, v63 offset0:12 offset1:28
	v_add_u32_e32 v59, 0x4000, v219
	ds_write2_b32 v59, v48, v52 offset0:64 offset1:80
	v_add_u32_e32 v48, 0x4400, v219
	ds_write2_b32 v48, v49, v53 offset0:68 offset1:84
	v_add_u32_e32 v49, 0x4800, v219
	ds_write2_b32 v49, v50, v54 offset0:72 offset1:88
	v_add_u32_e32 v50, 0x4c00, v219
	ds_write2_b32 v50, v51, v55 offset0:76 offset1:92
	v_add_u32_e32 v51, 0x8000, v219
	ds_write2_b32 v51, v32, v44 offset0:128 offset1:144
	v_add_u32_e32 v32, 0x8400, v219
	ds_write2_b32 v32, v33, v45 offset0:132 offset1:148
	v_add_u32_e32 v33, 0x8800, v219
	ds_write2_b32 v33, v34, v46 offset0:136 offset1:152
	v_add_u32_e32 v34, 0x8c00, v219
	ds_write2_b32 v34, v35, v47 offset0:140 offset1:156
	v_add_u32_e32 v35, 0xc000, v219
	ds_write2_b32 v35, v0, v12 offset0:192 offset1:208
	v_add_u32_e32 v0, 0xc400, v219
	ds_write2_b32 v0, v1, v13 offset0:196 offset1:212
	v_add_u32_e32 v1, 0xc800, v219
	ds_write2_b32 v1, v2, v14 offset0:200 offset1:216
	v_add_u32_e32 v2, 0xcc00, v219
	ds_write2_b32 v2, v3, v15 offset0:204 offset1:220
	ds_write2_b32 v219, v16, v36 offset0:128 offset1:144
	ds_write2_b32 v56, v17, v37 offset0:132 offset1:148
	ds_write2_b32 v57, v18, v38 offset0:136 offset1:152
	ds_write2_b32 v58, v19, v39 offset0:140 offset1:156
	ds_write2_b32 v59, v20, v40 offset0:192 offset1:208
	ds_write2_b32 v48, v21, v41 offset0:196 offset1:212
	ds_write2_b32 v49, v22, v42 offset0:200 offset1:216
	ds_write2_b32 v50, v23, v43 offset0:204 offset1:220
	ds_write2_b32 v32, v8, v28 offset1:16
	ds_write2_b32 v33, v9, v29 offset0:4 offset1:20
	ds_write2_b32 v34, v10, v30 offset0:8 offset1:24
	v_add_u32_e32 v3, 0x9000, v219
	ds_write2_b32 v3, v11, v31 offset0:12 offset1:28
	ds_write2_b32 v0, v4, v24 offset0:64 offset1:80
	ds_write2_b32 v1, v5, v25 offset0:68 offset1:84
	ds_write2_b32 v2, v6, v26 offset0:72 offset1:88
	v_add_u32_e32 v0, 0xd000, v219
	ds_write2_b32 v0, v7, v27 offset0:76 offset1:92
	s_mov_b32 s6, 0
	v_mov_b32_e32 v0, 0x358637bd
	s_mov_b32 s7, 0x800000
	s_waitcnt lgkmcnt(0)
	s_barrier
	global_load_dwordx4 v[72:75], v[64:65], off
	global_load_dwordx4 v[76:79], v[64:65], off offset:16
	v_add_u32_e32 v94, -4, v128
	v_ashrrev_i32_e32 v95, 31, v94
	v_lshl_add_u64 v[92:93], v[94:95], 2, s[2:3]
	v_lshlrev_b64 v[94:95], 12, v[94:95]
	global_load_dword v204, v[92:93], off sc1
	v_lshl_add_u64 v[94:95], v[66:67], 0, v[94:95]
	global_load_dwordx4 v[140:143], v[94:95], off
	global_load_dwordx4 v[144:147], v[94:95], off offset:16
	v_add_u32_e32 v94, 0, v128
	v_ashrrev_i32_e32 v95, 31, v94
	v_lshl_add_u64 v[92:93], v[94:95], 2, s[2:3]
	v_lshlrev_b64 v[94:95], 12, v[94:95]
	global_load_dword v205, v[92:93], off sc1
	v_lshl_add_u64 v[94:95], v[66:67], 0, v[94:95]
	global_load_dwordx4 v[148:151], v[94:95], off
	global_load_dwordx4 v[152:155], v[94:95], off offset:16
	v_add_u32_e32 v94, 4, v128
	v_ashrrev_i32_e32 v95, 31, v94
	v_lshl_add_u64 v[92:93], v[94:95], 2, s[2:3]
	v_lshlrev_b64 v[94:95], 12, v[94:95]
	global_load_dword v206, v[92:93], off sc1
	v_lshl_add_u64 v[94:95], v[66:67], 0, v[94:95]
	global_load_dwordx4 v[156:159], v[94:95], off
	global_load_dwordx4 v[160:163], v[94:95], off offset:16
	v_add_u32_e32 v94, 8, v128
	v_ashrrev_i32_e32 v95, 31, v94
	v_lshl_add_u64 v[92:93], v[94:95], 2, s[2:3]
	v_lshlrev_b64 v[94:95], 12, v[94:95]
	global_load_dword v207, v[92:93], off sc1
	v_lshl_add_u64 v[94:95], v[66:67], 0, v[94:95]
	global_load_dwordx4 v[164:167], v[94:95], off
	global_load_dwordx4 v[168:171], v[94:95], off offset:16
	v_add_u32_e32 v94, 12, v128
	v_ashrrev_i32_e32 v95, 31, v94
	v_lshl_add_u64 v[92:93], v[94:95], 2, s[2:3]
	v_lshlrev_b64 v[94:95], 12, v[94:95]
	global_load_dword v208, v[92:93], off sc1
	v_lshl_add_u64 v[94:95], v[66:67], 0, v[94:95]
	global_load_dwordx4 v[172:175], v[94:95], off
	global_load_dwordx4 v[176:179], v[94:95], off offset:16
	v_add_u32_e32 v94, 16, v128
	v_ashrrev_i32_e32 v95, 31, v94
	v_lshl_add_u64 v[92:93], v[94:95], 2, s[2:3]
	v_lshlrev_b64 v[94:95], 12, v[94:95]
	global_load_dword v209, v[92:93], off sc1
	v_lshl_add_u64 v[94:95], v[66:67], 0, v[94:95]
	global_load_dwordx4 v[180:183], v[94:95], off
	global_load_dwordx4 v[184:187], v[94:95], off offset:16
	v_add_u32_e32 v94, 20, v128
	v_ashrrev_i32_e32 v95, 31, v94
	v_lshl_add_u64 v[92:93], v[94:95], 2, s[2:3]
	v_lshlrev_b64 v[94:95], 12, v[94:95]
	global_load_dword v210, v[92:93], off sc1
	v_lshl_add_u64 v[94:95], v[66:67], 0, v[94:95]
	global_load_dwordx4 v[188:191], v[94:95], off
	global_load_dwordx4 v[192:195], v[94:95], off offset:16
	v_add_u32_e32 v94, 24, v128
	v_ashrrev_i32_e32 v95, 31, v94
	v_lshl_add_u64 v[92:93], v[94:95], 2, s[2:3]
	v_lshlrev_b64 v[94:95], 12, v[94:95]
	global_load_dword v211, v[92:93], off sc1
	v_lshl_add_u64 v[94:95], v[66:67], 0, v[94:95]
	global_load_dwordx4 v[196:199], v[94:95], off
	global_load_dwordx4 v[200:203], v[94:95], off offset:16
	ds_read_b128 v[80:83], v136 offset:0
	ds_read_b128 v[84:87], v136 offset:16
	v_add_u32_e32 v90, -4, v128
	v_ashrrev_i32_e32 v91, 31, v90
	v_lshlrev_b64 v[90:91], 12, v[90:91]
	v_lshl_add_u64 v[90:91], v[68:69], 0, v[90:91]
	s_waitcnt vmcnt(21)
	v_fmamk_f32 v88, v204, 0x3a800000, v0
	v_mul_f32_e32 v89, 0x4b800000, v88
	v_cmp_gt_f32_e32 vcc, s7, v88
	s_nop 1
	v_cndmask_b32_e32 v88, v88, v89, vcc
	v_rsq_f32_e32 v88, v88
	s_nop 0
	v_mul_f32_e32 v89, 0x45800000, v88
	v_cndmask_b32_e32 v88, v88, v89, vcc
	s_waitcnt lgkmcnt(0)
	v_pk_mul_f32 v[80:81], v[80:81], v[88:89] op_sel_hi:[1,0]
	v_pk_mul_f32 v[82:83], v[82:83], v[88:89] op_sel_hi:[1,0]
	v_pk_mul_f32 v[84:85], v[84:85], v[88:89] op_sel_hi:[1,0]
	v_pk_mul_f32 v[86:87], v[86:87], v[88:89] op_sel_hi:[1,0]
	v_pk_fma_f32 v[80:81], v[72:73], v[80:81], v[140:141]
	v_pk_fma_f32 v[82:83], v[74:75], v[82:83], v[142:143]
	v_pk_fma_f32 v[84:85], v[76:77], v[84:85], v[144:145]
	v_pk_fma_f32 v[86:87], v[78:79], v[86:87], v[146:147]
	global_store_dwordx4 v[90:91], v[80:83], off
	global_store_dwordx4 v[90:91], v[84:87], off offset:16
	ds_read_b128 v[96:99], v136 offset:4160
	ds_read_b128 v[100:103], v136 offset:4176
	v_add_u32_e32 v106, 0, v128
	v_ashrrev_i32_e32 v107, 31, v106
	v_lshlrev_b64 v[106:107], 12, v[106:107]
	v_lshl_add_u64 v[106:107], v[68:69], 0, v[106:107]
	s_waitcnt vmcnt(20)
	v_fmamk_f32 v104, v205, 0x3a800000, v0
	v_mul_f32_e32 v105, 0x4b800000, v104
	v_cmp_gt_f32_e32 vcc, s7, v104
	s_nop 1
	v_cndmask_b32_e32 v104, v104, v105, vcc
	v_rsq_f32_e32 v104, v104
	s_nop 0
	v_mul_f32_e32 v105, 0x45800000, v104
	v_cndmask_b32_e32 v104, v104, v105, vcc
	s_waitcnt lgkmcnt(0)
	v_pk_mul_f32 v[96:97], v[96:97], v[104:105] op_sel_hi:[1,0]
	v_pk_mul_f32 v[98:99], v[98:99], v[104:105] op_sel_hi:[1,0]
	v_pk_mul_f32 v[100:101], v[100:101], v[104:105] op_sel_hi:[1,0]
	v_pk_mul_f32 v[102:103], v[102:103], v[104:105] op_sel_hi:[1,0]
	v_pk_fma_f32 v[96:97], v[72:73], v[96:97], v[148:149]
	v_pk_fma_f32 v[98:99], v[74:75], v[98:99], v[150:151]
	v_pk_fma_f32 v[100:101], v[76:77], v[100:101], v[152:153]
	v_pk_fma_f32 v[102:103], v[78:79], v[102:103], v[154:155]
	global_store_dwordx4 v[106:107], v[96:99], off
	global_store_dwordx4 v[106:107], v[100:103], off offset:16
	ds_read_b128 v[80:83], v136 offset:8320
	ds_read_b128 v[84:87], v136 offset:8336
	v_add_u32_e32 v90, 4, v128
	v_ashrrev_i32_e32 v91, 31, v90
	v_lshlrev_b64 v[90:91], 12, v[90:91]
	v_lshl_add_u64 v[90:91], v[68:69], 0, v[90:91]
	s_waitcnt vmcnt(19)
	v_fmamk_f32 v88, v206, 0x3a800000, v0
	v_mul_f32_e32 v89, 0x4b800000, v88
	v_cmp_gt_f32_e32 vcc, s7, v88
	s_nop 1
	v_cndmask_b32_e32 v88, v88, v89, vcc
	v_rsq_f32_e32 v88, v88
	s_nop 0
	v_mul_f32_e32 v89, 0x45800000, v88
	v_cndmask_b32_e32 v88, v88, v89, vcc
	s_waitcnt lgkmcnt(0)
	v_pk_mul_f32 v[80:81], v[80:81], v[88:89] op_sel_hi:[1,0]
	v_pk_mul_f32 v[82:83], v[82:83], v[88:89] op_sel_hi:[1,0]
	v_pk_mul_f32 v[84:85], v[84:85], v[88:89] op_sel_hi:[1,0]
	v_pk_mul_f32 v[86:87], v[86:87], v[88:89] op_sel_hi:[1,0]
	v_pk_fma_f32 v[80:81], v[72:73], v[80:81], v[156:157]
	v_pk_fma_f32 v[82:83], v[74:75], v[82:83], v[158:159]
	v_pk_fma_f32 v[84:85], v[76:77], v[84:85], v[160:161]
	v_pk_fma_f32 v[86:87], v[78:79], v[86:87], v[162:163]
	global_store_dwordx4 v[90:91], v[80:83], off
	global_store_dwordx4 v[90:91], v[84:87], off offset:16
	ds_read_b128 v[96:99], v136 offset:12480
	ds_read_b128 v[100:103], v136 offset:12496
	v_add_u32_e32 v106, 8, v128
	v_ashrrev_i32_e32 v107, 31, v106
	v_lshlrev_b64 v[106:107], 12, v[106:107]
	v_lshl_add_u64 v[106:107], v[68:69], 0, v[106:107]
	s_waitcnt vmcnt(18)
	v_fmamk_f32 v104, v207, 0x3a800000, v0
	v_mul_f32_e32 v105, 0x4b800000, v104
	v_cmp_gt_f32_e32 vcc, s7, v104
	s_nop 1
	v_cndmask_b32_e32 v104, v104, v105, vcc
	v_rsq_f32_e32 v104, v104
	s_nop 0
	v_mul_f32_e32 v105, 0x45800000, v104
	v_cndmask_b32_e32 v104, v104, v105, vcc
	s_waitcnt lgkmcnt(0)
	v_pk_mul_f32 v[96:97], v[96:97], v[104:105] op_sel_hi:[1,0]
	v_pk_mul_f32 v[98:99], v[98:99], v[104:105] op_sel_hi:[1,0]
	v_pk_mul_f32 v[100:101], v[100:101], v[104:105] op_sel_hi:[1,0]
	v_pk_mul_f32 v[102:103], v[102:103], v[104:105] op_sel_hi:[1,0]
	v_pk_fma_f32 v[96:97], v[72:73], v[96:97], v[164:165]
	v_pk_fma_f32 v[98:99], v[74:75], v[98:99], v[166:167]
	v_pk_fma_f32 v[100:101], v[76:77], v[100:101], v[168:169]
	v_pk_fma_f32 v[102:103], v[78:79], v[102:103], v[170:171]
	global_store_dwordx4 v[106:107], v[96:99], off
	global_store_dwordx4 v[106:107], v[100:103], off offset:16
	ds_read_b128 v[80:83], v136 offset:16640
	ds_read_b128 v[84:87], v136 offset:16656
	v_add_u32_e32 v90, 12, v128
	v_ashrrev_i32_e32 v91, 31, v90
	v_lshlrev_b64 v[90:91], 12, v[90:91]
	v_lshl_add_u64 v[90:91], v[68:69], 0, v[90:91]
	s_waitcnt vmcnt(17)
	v_fmamk_f32 v88, v208, 0x3a800000, v0
	v_mul_f32_e32 v89, 0x4b800000, v88
	v_cmp_gt_f32_e32 vcc, s7, v88
	s_nop 1
	v_cndmask_b32_e32 v88, v88, v89, vcc
	v_rsq_f32_e32 v88, v88
	s_nop 0
	v_mul_f32_e32 v89, 0x45800000, v88
	v_cndmask_b32_e32 v88, v88, v89, vcc
	s_waitcnt lgkmcnt(0)
	v_pk_mul_f32 v[80:81], v[80:81], v[88:89] op_sel_hi:[1,0]
	v_pk_mul_f32 v[82:83], v[82:83], v[88:89] op_sel_hi:[1,0]
	v_pk_mul_f32 v[84:85], v[84:85], v[88:89] op_sel_hi:[1,0]
	v_pk_mul_f32 v[86:87], v[86:87], v[88:89] op_sel_hi:[1,0]
	v_pk_fma_f32 v[80:81], v[72:73], v[80:81], v[172:173]
	v_pk_fma_f32 v[82:83], v[74:75], v[82:83], v[174:175]
	v_pk_fma_f32 v[84:85], v[76:77], v[84:85], v[176:177]
	v_pk_fma_f32 v[86:87], v[78:79], v[86:87], v[178:179]
	global_store_dwordx4 v[90:91], v[80:83], off
	global_store_dwordx4 v[90:91], v[84:87], off offset:16
	ds_read_b128 v[96:99], v136 offset:20800
	ds_read_b128 v[100:103], v136 offset:20816
	v_add_u32_e32 v106, 16, v128
	v_ashrrev_i32_e32 v107, 31, v106
	v_lshlrev_b64 v[106:107], 12, v[106:107]
	v_lshl_add_u64 v[106:107], v[68:69], 0, v[106:107]
	s_waitcnt vmcnt(16)
	v_fmamk_f32 v104, v209, 0x3a800000, v0
	v_mul_f32_e32 v105, 0x4b800000, v104
	v_cmp_gt_f32_e32 vcc, s7, v104
	s_nop 1
	v_cndmask_b32_e32 v104, v104, v105, vcc
	v_rsq_f32_e32 v104, v104
	s_nop 0
	v_mul_f32_e32 v105, 0x45800000, v104
	v_cndmask_b32_e32 v104, v104, v105, vcc
	s_waitcnt lgkmcnt(0)
	v_pk_mul_f32 v[96:97], v[96:97], v[104:105] op_sel_hi:[1,0]
	v_pk_mul_f32 v[98:99], v[98:99], v[104:105] op_sel_hi:[1,0]
	v_pk_mul_f32 v[100:101], v[100:101], v[104:105] op_sel_hi:[1,0]
	v_pk_mul_f32 v[102:103], v[102:103], v[104:105] op_sel_hi:[1,0]
	v_pk_fma_f32 v[96:97], v[72:73], v[96:97], v[180:181]
	v_pk_fma_f32 v[98:99], v[74:75], v[98:99], v[182:183]
	v_pk_fma_f32 v[100:101], v[76:77], v[100:101], v[184:185]
	v_pk_fma_f32 v[102:103], v[78:79], v[102:103], v[186:187]
	global_store_dwordx4 v[106:107], v[96:99], off
	global_store_dwordx4 v[106:107], v[100:103], off offset:16
	ds_read_b128 v[80:83], v136 offset:24960
	ds_read_b128 v[84:87], v136 offset:24976
	v_add_u32_e32 v90, 20, v128
	v_ashrrev_i32_e32 v91, 31, v90
	v_lshlrev_b64 v[90:91], 12, v[90:91]
	v_lshl_add_u64 v[90:91], v[68:69], 0, v[90:91]
	s_waitcnt vmcnt(15)
	v_fmamk_f32 v88, v210, 0x3a800000, v0
	v_mul_f32_e32 v89, 0x4b800000, v88
	v_cmp_gt_f32_e32 vcc, s7, v88
	s_nop 1
	v_cndmask_b32_e32 v88, v88, v89, vcc
	v_rsq_f32_e32 v88, v88
	s_nop 0
	v_mul_f32_e32 v89, 0x45800000, v88
	v_cndmask_b32_e32 v88, v88, v89, vcc
	s_waitcnt lgkmcnt(0)
	v_pk_mul_f32 v[80:81], v[80:81], v[88:89] op_sel_hi:[1,0]
	v_pk_mul_f32 v[82:83], v[82:83], v[88:89] op_sel_hi:[1,0]
	v_pk_mul_f32 v[84:85], v[84:85], v[88:89] op_sel_hi:[1,0]
	v_pk_mul_f32 v[86:87], v[86:87], v[88:89] op_sel_hi:[1,0]
	v_pk_fma_f32 v[80:81], v[72:73], v[80:81], v[188:189]
	v_pk_fma_f32 v[82:83], v[74:75], v[82:83], v[190:191]
	v_pk_fma_f32 v[84:85], v[76:77], v[84:85], v[192:193]
	v_pk_fma_f32 v[86:87], v[78:79], v[86:87], v[194:195]
	global_store_dwordx4 v[90:91], v[80:83], off
	global_store_dwordx4 v[90:91], v[84:87], off offset:16
	ds_read_b128 v[96:99], v136 offset:29120
	ds_read_b128 v[100:103], v136 offset:29136
	v_add_u32_e32 v106, 24, v128
	v_ashrrev_i32_e32 v107, 31, v106
	v_lshlrev_b64 v[106:107], 12, v[106:107]
	v_lshl_add_u64 v[106:107], v[68:69], 0, v[106:107]
	s_waitcnt vmcnt(14)
	v_fmamk_f32 v104, v211, 0x3a800000, v0
	v_mul_f32_e32 v105, 0x4b800000, v104
	v_cmp_gt_f32_e32 vcc, s7, v104
	s_nop 1
	v_cndmask_b32_e32 v104, v104, v105, vcc
	v_rsq_f32_e32 v104, v104
	s_nop 0
	v_mul_f32_e32 v105, 0x45800000, v104
	v_cndmask_b32_e32 v104, v104, v105, vcc
	s_waitcnt lgkmcnt(0)
	v_pk_mul_f32 v[96:97], v[96:97], v[104:105] op_sel_hi:[1,0]
	v_pk_mul_f32 v[98:99], v[98:99], v[104:105] op_sel_hi:[1,0]
	v_pk_mul_f32 v[100:101], v[100:101], v[104:105] op_sel_hi:[1,0]
	v_pk_mul_f32 v[102:103], v[102:103], v[104:105] op_sel_hi:[1,0]
	v_pk_fma_f32 v[96:97], v[72:73], v[96:97], v[196:197]
	v_pk_fma_f32 v[98:99], v[74:75], v[98:99], v[198:199]
	v_pk_fma_f32 v[100:101], v[76:77], v[100:101], v[200:201]
	v_pk_fma_f32 v[102:103], v[78:79], v[102:103], v[202:203]
	global_store_dwordx4 v[106:107], v[96:99], off
	global_store_dwordx4 v[106:107], v[100:103], off offset:16
	s_branch .LBB0_616
